# MLA interior loop as two-group ping-pong: waves 4-7 run half an iteration behind waves 0-3 (second barrier mid-body, DMA share of waves 4-7 issued at their softmax start)
# speedup vs baseline: 1.0044x; 1.0044x over previous
.LBB0_347:
	s_lshl_b64 s[0:1], s[50:51], 1
	s_mov_b64 s[2:3], s[10:11]
	s_add_u32 s10, s2, s0
	s_addc_u32 s11, s3, s1
	v_readlane_b32 s4, v255, 34
	v_readlane_b32 s5, v255, 35
	s_add_u32 s12, s4, s0
	s_addc_u32 s13, s5, s1
	s_lshl_b64 s[0:1], s[52:53], 1
	s_add_u32 s0, s2, s0
	s_addc_u32 s1, s3, s1
	v_lshl_add_u64 v[30:31], s[0:1], 0, v[112:113]
	s_mov_b32 s0, 2
	s_cmp_lt_u32 s22, 6
	v_cmp_gt_u32_e64 s[40:41], 32, v191
	v_add_u32_e32 v112, s14, v114
	v_lshl_add_u32 v198, v193, 2, s15
	v_lshl_add_u32 v1, v199, 2, s15
	s_waitcnt lgkmcnt(0)
	s_barrier
	s_cbranch_scc1 .LBB0_359
	v_add_u32_e32 v114, 0xc0, v112
	v_or_b32_e32 v170, 0xc0, v191
	s_mov_b32 s2, 5
	v_readfirstlane_b32 s100, v195
	v_mov_b32_e32 v218, v170
	v_ashrrev_i32_e32 v219, 31, v170
	v_lshlrev_b64 v[216:217], 11, v[218:219]
	v_lshlrev_b64 v[218:219], 9, v[218:219]
	v_lshl_add_u64 v[216:217], s[10:11], 0, v[216:217]
	v_lshl_add_u64 v[218:219], s[12:13], 0, v[218:219]
	s_add_i32 s0, s2, -1
	s_and_b32 s0, s0, 1
	s_mulk_i32 s0, 0x5100
	s_add_i32 s101, s100, s0
	s_and_b64 vcc, exec, s[38:39]
	s_cbranch_vccz .Lpp_entryA
	s_mov_b32 m0, s101
	v_ashrrev_i32_e32 v115, 31, v114
	global_load_lds_dwordx4 v[216:217], off
	v_lshlrev_b64 v[22:23], 11, v[114:115]
	s_add_i32 m0, s101, 0x2f80
	v_lshl_add_u64 v[26:27], v[30:31], 0, v[22:23]
	global_load_lds_dwordx4 v[26:27], off offset:128
	s_barrier
.Lpp_entryA:
	s_branch .LBB0_350
.LBB0_349:
	v_pk_add_f32 v[66:67], v[66:67], v[200:201]
	v_pk_add_f32 v[68:69], v[68:69], v[6:7]
	v_pk_add_f32 v[70:71], v[70:71], v[8:9]
	v_pk_add_f32 v[72:73], v[72:73], v[10:11]
	v_pk_add_f32 v[74:75], v[74:75], v[12:13]
	v_pk_add_f32 v[76:77], v[76:77], v[14:15]
	v_pk_add_f32 v[78:79], v[78:79], v[16:17]
	v_add_f32_e32 v3, v64, v115
	v_add_f32_e32 v4, v65, v171
	v_pk_add_f32 v[66:67], v[66:67], v[68:69]
	v_pk_add_f32 v[70:71], v[70:71], v[72:73]
	v_pk_add_f32 v[74:75], v[74:75], v[76:77]
	v_add_f32_e32 v3, v3, v4
	v_pk_add_f32 v[66:67], v[66:67], v[70:71]
	v_pk_add_f32 v[74:75], v[74:75], v[78:79]
	v_pk_add_f32 v[66:67], v[66:67], v[74:75]
	v_add_f32_e32 v3, v3, v66
	v_add_f32_e32 v3, v3, v67
	s_add_i32 s2, s2, 1
	v_add_f32_e32 v163, v163, v3
	s_and_b64 vcc, exec, s[38:39]
	s_cbranch_vccnz .Lpp_noinc
	v_add_u32_e32 v114, 64, v114
	v_add_u32_e32 v170, 64, v170
.Lpp_noinc:
	s_add_i32 s0, s2, -1
	s_and_b32 s0, s0, 1
	s_mulk_i32 s0, 0x5100
	s_add_i32 s101, s100, s0
	v_mov_b32_e32 v218, v170
	v_ashrrev_i32_e32 v219, 31, v170
	v_lshlrev_b64 v[216:217], 11, v[218:219]
	v_lshlrev_b64 v[218:219], 9, v[218:219]
	v_lshl_add_u64 v[216:217], s[10:11], 0, v[216:217]
	v_lshl_add_u64 v[218:219], s[12:13], 0, v[218:219]
	s_cmp_eq_u32 s22, s2
	s_cbranch_vccnz .Lpp_nowait
	s_waitcnt vmcnt(0)
.Lpp_nowait:
	s_waitcnt lgkmcnt(0)
	s_barrier
	s_cbranch_scc1 .LBB0_358
.LBB0_350:
	s_add_i32 s0, s2, -1
	s_and_b32 s3, s0, 1
	s_xor_b32 s0, s3, 1
	s_mulk_i32 s0, 0x5100
	v_add_u32_e32 v84, s0, v197
	ds_read_b128 v[18:21], v84
	ds_read_b128 v[22:25], v84 offset:512
	s_and_b64 vcc, exec, s[38:39]
	s_cbranch_vccnz .LBB0_352
	s_mov_b32 m0, s101
	v_ashrrev_i32_e32 v115, 31, v114
	global_load_lds_dwordx4 v[216:217], off
	s_add_i32 m0, s101, 0x2000
	s_nop 0
	global_load_lds_dwordx4 v[218:219], off
.LBB0_352:
	s_waitcnt lgkmcnt(1)
	v_mfma_f32_32x32x16_bf16 v[2:17], v[18:21], v[116:119], v[96:111]
	s_waitcnt lgkmcnt(0)
	v_mfma_f32_32x32x16_bf16 v[64:79], v[22:25], v[116:119], v[96:111]
	ds_read_b128 v[18:21], v84 offset:2048
	ds_read_b128 v[22:25], v84 offset:2560
	s_waitcnt lgkmcnt(0)
	v_mfma_f32_32x32x16_bf16 v[64:79], v[22:25], v[120:123], v[64:79]
	v_mfma_f32_32x32x16_bf16 v[2:17], v[18:21], v[120:123], v[2:17]
	ds_read_b128 v[18:21], v84 offset:4096
	ds_read_b128 v[22:25], v84 offset:4608
	s_waitcnt lgkmcnt(0)
	v_mfma_f32_32x32x16_bf16 v[64:79], v[22:25], v[124:127], v[64:79]
	v_mfma_f32_32x32x16_bf16 v[2:17], v[18:21], v[124:127], v[2:17]
	ds_read_b128 v[18:21], v84 offset:6144
	ds_read_b128 v[22:25], v84 offset:6656
	s_waitcnt lgkmcnt(0)
	v_mfma_f32_32x32x16_bf16 v[64:79], v[22:25], v[128:131], v[64:79]
	s_and_b64 vcc, exec, s[38:39]
	s_cbranch_vccnz .Lpp_noV
	v_lshlrev_b64 v[22:23], 11, v[114:115]
	s_add_i32 m0, s101, 0x2f80
	v_lshl_add_u64 v[26:27], v[30:31], 0, v[22:23]
	global_load_lds_dwordx4 v[26:27], off offset:128
.Lpp_noV:
	ds_read_b128 v[22:25], v84 offset:8704
	ds_read_b128 v[26:29], v84 offset:10240
	v_add_u32_e32 v115, s0, v196
	v_mfma_f32_32x32x16_bf16 v[2:17], v[18:21], v[128:131], v[2:17]
	ds_read_b128 v[18:21], v84 offset:8192
	s_waitcnt lgkmcnt(0)
	v_mfma_f32_32x32x16_bf16 v[2:17], v[18:21], v[132:135], v[2:17]
	ds_read_b64_tr_b16 v[152:153], v115 offset:12288
	ds_read_b64_tr_b16 v[154:155], v115 offset:12800
	ds_read_b64_tr_b16 v[88:89], v115 offset:13312
	ds_read_b64_tr_b16 v[90:91], v115 offset:13824
	ds_read_b64_tr_b16 v[80:81], v115 offset:14336
	ds_read_b64_tr_b16 v[82:83], v115 offset:14848
	ds_read_b64_tr_b16 v[18:19], v115 offset:15360
	ds_read_b64_tr_b16 v[20:21], v115 offset:15872
	ds_read_b128 v[200:203], v84 offset:10752
	v_mfma_f32_32x32x16_bf16 v[64:79], v[22:25], v[132:135], v[64:79]
	v_mfma_f32_32x32x16_bf16 v[2:17], v[26:29], v[136:139], v[2:17]
	ds_read_b64_tr_b16 v[92:93], v115 offset:16384
	ds_read_b64_tr_b16 v[94:95], v115 offset:16896
	ds_read_b64_tr_b16 v[84:85], v115 offset:17408
	ds_read_b64_tr_b16 v[86:87], v115 offset:17920
	ds_read_b64_tr_b16 v[26:27], v115 offset:18432
	ds_read_b64_tr_b16 v[28:29], v115 offset:18944
	ds_read_b64_tr_b16 v[22:23], v115 offset:19456
	ds_read_b64_tr_b16 v[24:25], v115 offset:19968
	s_waitcnt lgkmcnt(8)
	v_mfma_f32_32x32x16_bf16 v[64:79], v[200:203], v[136:139], v[64:79]
	s_and_b64 vcc, exec, s[38:39]
	s_cbranch_vccnz .Lpp_midB
	s_barrier
	s_branch .Lpp_mid_done
.Lpp_midB:
	s_waitcnt vmcnt(0) lgkmcnt(0)
	s_barrier
	v_add_u32_e32 v114, 64, v114
	v_add_u32_e32 v170, 64, v170
	s_add_i32 s1, s2, 1
	s_cmp_eq_u32 s1, s22
	s_cbranch_scc1 .Lpp_mid_done
	v_mov_b32_e32 v216, v170
	v_ashrrev_i32_e32 v217, 31, v170
	v_mov_b32_e32 v204, v114
	v_ashrrev_i32_e32 v205, 31, v114
	s_and_b32 s0, s2, 1
	v_lshlrev_b64 v[216:217], 11, v[216:217]
	v_lshlrev_b64 v[204:205], 11, v[204:205]
	s_mulk_i32 s0, 0x5100
	v_lshl_add_u64 v[216:217], s[10:11], 0, v[216:217]
	v_lshl_add_u64 v[204:205], v[30:31], 0, v[204:205]
	s_add_i32 s0, s100, s0
	s_mov_b32 m0, s0
	s_nop 0
	global_load_lds_dwordx4 v[216:217], off
	s_add_i32 m0, s0, 0x2f80
	s_nop 0
	global_load_lds_dwordx4 v[204:205], off offset:128
.Lpp_mid_done:
	v_max3_f32 v115, v2, v3, v64
	v_max3_f32 v171, v4, v5, v65
	v_max3_f32 v115, v115, v66, v67
	v_max3_f32 v171, v171, v8, v9
	v_max3_f32 v115, v115, v6, v7
	v_max3_f32 v171, v171, v70, v71
	v_max3_f32 v115, v115, v68, v69
	v_max3_f32 v171, v171, v12, v13
	v_max3_f32 v115, v115, v10, v11
	v_max3_f32 v171, v171, v74, v75
	v_max3_f32 v115, v115, v72, v73
	v_max3_f32 v171, v171, v16, v17
	v_max3_f32 v115, v115, v14, v15
	v_max3_f32 v171, v171, v78, v79
	v_max3_f32 v115, v115, v76, v77
	v_max_f32_e32 v115, v115, v171
	v_mov_b32_e32 v171, v115
	s_nop 1
	v_permlane32_swap_b32_e32 v115, v171
	v_max_f32_e32 v115, v115, v171
	v_cmp_lt_f32_e32 vcc, s75, v115
	s_cbranch_vccz .LBB0_356
	v_max_f32_e32 v96, v115, v115
	v_max_f32_e32 v98, 0, v96
	v_exp_f32_e64 v115, -v98
	s_and_saveexec_b64 s[0:1], s[40:41]
	ds_write_b32 v198, v115 offset:41472
	s_or_b64 exec, exec, s[0:1]
	s_waitcnt lgkmcnt(0)
	ds_read_b128 v[200:203], v1 offset:41472
	ds_read_b128 v[204:207], v1 offset:41504
	ds_read_b128 v[208:211], v1 offset:41536
	ds_read_b128 v[212:215], v1 offset:41568
	v_add_f32_e32 v0, v0, v98
	s_waitcnt lgkmcnt(0)
	v_xor_b32_e32 v96, 0x80000000, v0
	v_pk_add_f32 v[2:3], v[2:3], v[98:99] op_sel_hi:[1,0] neg_lo:[0,1] neg_hi:[0,1]
	v_pk_add_f32 v[64:65], v[64:65], v[98:99] op_sel_hi:[1,0] neg_lo:[0,1] neg_hi:[0,1]
	v_pk_add_f32 v[4:5], v[4:5], v[98:99] op_sel_hi:[1,0] neg_lo:[0,1] neg_hi:[0,1]
	v_pk_add_f32 v[66:67], v[66:67], v[98:99] op_sel_hi:[1,0] neg_lo:[0,1] neg_hi:[0,1]
	v_pk_add_f32 v[6:7], v[6:7], v[98:99] op_sel_hi:[1,0] neg_lo:[0,1] neg_hi:[0,1]
	v_pk_add_f32 v[68:69], v[68:69], v[98:99] op_sel_hi:[1,0] neg_lo:[0,1] neg_hi:[0,1]
	v_pk_add_f32 v[8:9], v[8:9], v[98:99] op_sel_hi:[1,0] neg_lo:[0,1] neg_hi:[0,1]
	v_pk_add_f32 v[70:71], v[70:71], v[98:99] op_sel_hi:[1,0] neg_lo:[0,1] neg_hi:[0,1]
	v_pk_add_f32 v[10:11], v[10:11], v[98:99] op_sel_hi:[1,0] neg_lo:[0,1] neg_hi:[0,1]
	v_pk_add_f32 v[72:73], v[72:73], v[98:99] op_sel_hi:[1,0] neg_lo:[0,1] neg_hi:[0,1]
	v_pk_add_f32 v[12:13], v[12:13], v[98:99] op_sel_hi:[1,0] neg_lo:[0,1] neg_hi:[0,1]
	v_pk_add_f32 v[74:75], v[74:75], v[98:99] op_sel_hi:[1,0] neg_lo:[0,1] neg_hi:[0,1]
	v_pk_add_f32 v[14:15], v[14:15], v[98:99] op_sel_hi:[1,0] neg_lo:[0,1] neg_hi:[0,1]
	v_pk_add_f32 v[76:77], v[76:77], v[98:99] op_sel_hi:[1,0] neg_lo:[0,1] neg_hi:[0,1]
	v_pk_add_f32 v[16:17], v[16:17], v[98:99] op_sel_hi:[1,0] neg_lo:[0,1] neg_hi:[0,1]
	v_pk_add_f32 v[78:79], v[78:79], v[98:99] op_sel_hi:[1,0] neg_lo:[0,1] neg_hi:[0,1]
	v_mov_b32_e32 v97, v96
	v_mov_b32_e32 v98, v96
	v_mov_b32_e32 v99, v96
	v_mov_b32_e32 v100, v96
	v_mov_b32_e32 v101, v96
	v_mov_b32_e32 v102, v96
	v_mov_b32_e32 v103, v96
	v_mov_b32_e32 v104, v96
	v_mov_b32_e32 v105, v96
	v_mov_b32_e32 v106, v96
	v_mov_b32_e32 v107, v96
	v_mov_b32_e32 v108, v96
	v_mov_b32_e32 v109, v96
	v_mov_b32_e32 v110, v96
	v_mov_b32_e32 v111, v96
	v_mul_f32_e32 v163, v163, v115
	s_waitcnt lgkmcnt(0)
	v_pk_mul_f32 v[46:47], v[46:47], v[214:215]
	v_pk_mul_f32 v[42:43], v[42:43], v[210:211]
	v_pk_mul_f32 v[38:39], v[38:39], v[206:207]
	v_pk_mul_f32 v[34:35], v[34:35], v[202:203]
	v_pk_mul_f32 v[44:45], v[44:45], v[212:213]
	v_pk_mul_f32 v[40:41], v[40:41], v[208:209]
	v_pk_mul_f32 v[36:37], v[36:37], v[204:205]
	v_pk_mul_f32 v[32:33], v[32:33], v[200:201]
	v_pk_mul_f32 v[62:63], v[62:63], v[214:215]
	v_pk_mul_f32 v[58:59], v[58:59], v[210:211]
	v_pk_mul_f32 v[54:55], v[54:55], v[206:207]
	v_pk_mul_f32 v[50:51], v[50:51], v[202:203]
	v_pk_mul_f32 v[60:61], v[60:61], v[212:213]
	v_pk_mul_f32 v[56:57], v[56:57], v[208:209]
	v_pk_mul_f32 v[52:53], v[52:53], v[204:205]
	v_pk_mul_f32 v[48:49], v[48:49], v[200:201]

.LBB0_358:
	s_and_b64 vcc, exec, s[38:39]
	s_cbranch_vccnz .Lpp_exitB
	s_barrier
